# FoX attention loop software-pipelined: PV(t-1)/QK(t+1) MFMAs interleaved into softmax(t) VALU; K prefetch 3 tiles, V 1 tile
# baseline (speedup 1.0000x reference)
; #define LAS __attribute__((address_space(3)))
; template <int DQK, int DV, bool FOX> ...
;     ...
;     f32x16 o[NCB];
; #pragma unroll
;     for (int cb = 0; cb < NCB; ++cb)
; #pragma unroll
;         for (int i = 0; i < 16; ++i) o[cb][i] = 0.f;
;     float mref = -1e30f, lsum = 0.f;
;     const int kread0 = r * KROW;
;     const int ksw = (r >> 1) & 7;
;     const int vread0 = KT_BYTES + ((lane >> 4) & 1) * 32 + (lane & 3) * 8 + (4 * h + ((lane & 15) >> 2)) * 64;
;     ...
;     ATT_DMA(0, 0); ATT_DMA(1, 1); ATT_WAIT_TILE(); __builtin_amdgcn_s_barrier();
; #pragma unroll
;     for (int d0 = 0; d0 < ND0; ++d0) asm volatile("" : "+v"(qf[d0]));
;     if (FOX) asm volatile("" : "+v"(cq), "+v"(basev));
;     int bc = 0, bn2 = 2;
;     for (int t = 0; t < NT; ++t) {
;         if (t + 2 < NT) ATT_DMA(t + 2, bn2);
;         if (t < ntw) {
;             LAS unsigned char* b = lds + bc * BUF_STRIDE;
;             f32x16 p0, p1;
;             if (FOX) {
;                 const LAS float* ck = (const LAS float*)(b + KT_BYTES + VT_BYTES);
; #pragma unroll
;                 for (int g = 0; g < 4; ++g) { const f32x4 c0 = *(const LAS f32x4*)(ck + 8 * g + 4 * h), c1 = *(const LAS f32x4*)(ck + 32 + 8 * g + 4 * h);
; #pragma unroll
;                     for (int e = 0; e < 4; ++e) { p0[4 * g + e] = c0[e]; p1[4 * g + e] = c1[e]; } }
;             } else {
; #pragma unroll
;             for (int i = 0; i < 16; ++i) { p0[i] = 0.f; p1[i] = 0.f; }
;             }
;             {
;                 constexpr int GB = FOX ? 4 : 3;
; #pragma unroll
;                 for (int g0 = 0; g0 < ND0; g0 += GB) { bf16x8 ka[GB], kb[GB];
; #pragma unroll
;                     for (int j = 0; j < GB; ++j) { const int c = 2 * (g0 + j) + h; const int co = ((c & ~7) | ((c ^ ksw) & 7)) * 16;
;                         ka[j] = *(const LAS bf16x8*)(b + kread0 + co); kb[j] = *(const LAS bf16x8*)(b + kread0 + 32 * KROW + co); }
;                     __builtin_amdgcn_sched_barrier(0);
; #pragma unroll
;                     for (int j = 0; j < GB; ++j) { p0 = __builtin_amdgcn_mfma_f32_32x32x16_bf16(ka[j], qf[g0 + j], p0, 0, 0, 0);
;                                                    p1 = __builtin_amdgcn_mfma_f32_32x32x16_bf16(kb[j], qf[g0 + j], p1, 0, 0, 0); }
;                     __builtin_amdgcn_sched_barrier(0); } }
.LBB0_655:
	v_mov_b32_e32 v3, v151
	v_lshl_add_u64 v[98:99], s[2:3], 0, v[2:3]
	v_and_or_b32 v2, s4, 32, v146
	v_or_b32_e32 v3, 32, v147
	s_add_i32 s1, s5, 4
	s_lshl_b32 s5, s16, 2
	s_waitcnt vmcnt(4)
	v_add_f32_e32 v109, s17, v10
	v_cmp_gt_u32_e64 s[16:17], v3, v2
	v_or_b32_e32 v3, 33, v147
	v_cmp_gt_u32_e64 s[20:21], v3, v2
	v_or_b32_e32 v3, 2, v147
	v_cmp_gt_u32_e64 s[22:23], v3, v2
	v_or_b32_e32 v3, 34, v147
	v_cmp_gt_u32_e64 s[24:25], v3, v2
	v_or_b32_e32 v3, 3, v147
	v_cmp_gt_u32_e64 s[26:27], v3, v2
	v_or_b32_e32 v3, 35, v147
	v_cmp_gt_u32_e64 s[28:29], v3, v2
	v_or_b32_e32 v3, 8, v147
	v_cmp_gt_u32_e64 s[30:31], v3, v2
	v_or_b32_e32 v3, 40, v147
	v_cmp_gt_u32_e64 s[34:35], v3, v2
	v_or_b32_e32 v3, 9, v147
	v_cmp_gt_u32_e64 s[36:37], v3, v2
	v_or_b32_e32 v3, 41, v147
	v_cmp_gt_u32_e64 s[38:39], v3, v2
	v_or_b32_e32 v3, 42, v147
	v_cmp_gt_u32_e64 s[42:43], v3, v2
	v_or_b32_e32 v3, 43, v147
	v_cmp_gt_u32_e64 s[46:47], v3, v2
	v_or_b32_e32 v3, 48, v147
	v_cmp_gt_u32_e64 s[50:51], v3, v2
	v_or_b32_e32 v3, 49, v147
	v_cmp_gt_u32_e64 s[54:55], v3, v2
	v_or_b32_e32 v3, 50, v147
	v_cmp_gt_u32_e64 s[58:59], v3, v2
	v_or_b32_e32 v3, 51, v147
	v_cmp_gt_u32_e64 s[62:63], v3, v2
	v_or_b32_e32 v3, 56, v147
	v_cmp_gt_u32_e64 s[66:67], v3, v2
	v_or_b32_e32 v3, 57, v147
	s_add_i32 s5, s5, 0
	v_cmp_gt_u32_e64 s[70:71], v3, v2
	v_or_b32_e32 v3, 58, v147
	s_add_i32 s5, s5, 0x1e300
	v_cmp_gt_u32_e64 s[74:75], v3, v2
	v_or_b32_e32 v3, 59, v147
	s_mov_b64 s[2:3], 0x200000
	v_mov_b32_e32 v110, 0
	s_mov_b32 s7, 2
	v_lshl_add_u32 v108, v146, 2, s5
	v_lshl_add_u32 v106, v147, 2, s5
	v_cmp_gt_u32_e64 s[14:15], v147, v2
	v_cmp_lt_u32_e64 s[18:19], v147, v2
	v_cmp_gt_u32_e64 s[40:41], v218, v2
	v_cmp_gt_u32_e64 s[44:45], v219, v2
	v_cmp_gt_u32_e64 s[48:49], v220, v2
	v_cmp_gt_u32_e64 s[52:53], v221, v2
	v_cmp_gt_u32_e64 s[56:57], v222, v2
	v_cmp_gt_u32_e64 s[60:61], v223, v2
	v_cmp_gt_u32_e64 s[64:65], v224, v2
	v_cmp_gt_u32_e64 s[68:69], v225, v2
	v_cmp_gt_u32_e64 s[72:73], v226, v2
	v_cmp_gt_u32_e64 s[76:77], v227, v2
	v_cmp_gt_u32_e64 s[78:79], v3, v2
	v_lshl_add_u64 v[100:101], v[4:5], 0, s[94:95]
	v_lshl_add_u64 v[102:103], v[6:7], 0, s[2:3]
	s_mov_b32 s86, 0
	v_mov_b32_e32 v111, 0xf149f2ca
	s_movk_i32 s84, 0x80
	s_mov_b32 s87, 0
	v_mov_b32_e32 v2, 0
	v_mov_b32_e32 v3, v110
	v_mov_b32_e32 v4, v110
	v_mov_b32_e32 v5, v110
	v_mov_b32_e32 v6, v110
	v_mov_b32_e32 v7, v110
	v_mov_b32_e32 v8, v110
	v_mov_b32_e32 v9, v110
	v_mov_b32_e32 v10, v110
	v_mov_b32_e32 v11, v110
	v_mov_b32_e32 v12, v110
	v_mov_b32_e32 v13, v110
	v_mov_b32_e32 v14, v110
	v_mov_b32_e32 v15, v110
	v_mov_b32_e32 v16, v110
	v_mov_b32_e32 v17, v110
	v_mov_b32_e32 v18, v110
	v_mov_b32_e32 v19, v110
	v_mov_b32_e32 v20, v110
	v_mov_b32_e32 v21, v110
	v_mov_b32_e32 v22, v110
	v_mov_b32_e32 v23, v110
	v_mov_b32_e32 v24, v110
	v_mov_b32_e32 v25, v110
	v_mov_b32_e32 v26, v110
	v_mov_b32_e32 v27, v110
	v_mov_b32_e32 v28, v110
	v_mov_b32_e32 v29, v110
	v_mov_b32_e32 v30, v110
	v_mov_b32_e32 v31, v110
	v_mov_b32_e32 v32, v110
	v_mov_b32_e32 v33, v110
	s_barrier
	s_waitcnt vmcnt(3)
	s_waitcnt vmcnt(2)
	s_waitcnt vmcnt(1)
	s_waitcnt vmcnt(0)
	s_add_i32 s5, s33, 0x14200
	s_mov_b32 s88, m0
	s_mov_b32 m0, s5
	s_nop 0
	global_load_lds_dwordx4 v[102:103], off
	s_mov_b32 m0, s88
	s_andn2_b64 vcc, exec, s[96:97]
	s_cbranch_vccnz .Lfp_pro_nock
	s_mov_b32 s5, 0x18200
	v_lshl_add_u64 v[130:131], s[84:85], 2, v[98:99]
	s_mov_b32 s88, m0
	s_mov_b32 m0, s5
	s_nop 0
	global_load_lds_dword v[130:131], off
	s_mov_b32 m0, s88
.Lfp_pro_nock:
	v_lshl_add_u64 v[102:103], v[102:103], 0, s[94:95]
	s_movk_i32 s84, 0xc0
	s_mov_b32 s100, 0
	v_lshlrev_b32_e32 v214, 2, v147
	ds_read_b128 v[50:53], v214 offset:16384
	ds_read_b128 v[54:57], v214 offset:16416
	ds_read_b128 v[58:61], v214 offset:16448
	ds_read_b128 v[62:65], v214 offset:16480
	ds_read_b128 v[34:37], v214 offset:16512
	ds_read_b128 v[38:41], v214 offset:16544
	ds_read_b128 v[42:45], v214 offset:16576
	ds_read_b128 v[46:49], v214 offset:16608
	s_mov_b32 s6, 0
	v_lshlrev_b32_e32 v215, 7, v146
	v_add_u32_e32 v215, s6, v215
	v_add_u32_e32 v86, v215, v197
	v_add_u32_e32 v94, v215, v211
	v_add_u32_e32 v116, v215, v212
	v_add_u32_e32 v215, v215, v213
	ds_read_b128 v[82:85], v86
	ds_read_b128 v[90:93], v94
	ds_read_b128 v[112:115], v116
	ds_read_b128 v[120:123], v215
	ds_read_b128 v[86:89], v86 offset:4096
	ds_read_b128 v[94:97], v94 offset:4096
	ds_read_b128 v[116:119], v116 offset:4096
	ds_read_b128 v[124:127], v215 offset:4096
	s_waitcnt lgkmcnt(7)
	v_mfma_f32_32x32x16_bf16 v[50:65], v[82:85], v[66:69], v[50:65]
	s_waitcnt lgkmcnt(6)
	v_mfma_f32_32x32x16_bf16 v[50:65], v[90:93], v[70:73], v[50:65]
	s_waitcnt lgkmcnt(5)
	v_mfma_f32_32x32x16_bf16 v[50:65], v[112:115], v[74:77], v[50:65]
	s_waitcnt lgkmcnt(4)
	v_mfma_f32_32x32x16_bf16 v[50:65], v[120:123], v[78:81], v[50:65]
	s_waitcnt lgkmcnt(3)
	v_mfma_f32_32x32x16_bf16 v[34:49], v[86:89], v[66:69], v[34:49]
	s_waitcnt lgkmcnt(2)
	v_mfma_f32_32x32x16_bf16 v[34:49], v[94:97], v[70:73], v[34:49]
	s_waitcnt lgkmcnt(1)
	v_mfma_f32_32x32x16_bf16 v[34:49], v[116:119], v[74:77], v[34:49]
	s_waitcnt lgkmcnt(0)
	v_mfma_f32_32x32x16_bf16 v[34:49], v[124:127], v[78:81], v[34:49]
	s_waitcnt lgkmcnt(0)
	s_barrier
	s_branch .Lfp_loop
.Lfp_latch:
	s_add_i32 s2, s86, 1
	s_cmp_lg_u32 s86, 2
	s_cselect_b32 s86, s2, 0
	s_add_i32 s87, s87, 1
	s_add_i32 s84, s84, 64
	v_lshl_add_u64 v[100:101], v[100:101], 0, s[94:95]
	v_lshl_add_u64 v[102:103], v[102:103], 0, s[94:95]
	s_cmp_gt_u32 s87, s1
	s_cbranch_scc1 .LBB0_676
; template <int DQK, int DV, bool FOX> ...
;     ...
;             float rm = fmaxf(fmaxf(p0[0], p1[0]), p0[1]);
; #pragma unroll
;             for (int i = 1; i < 15; ++i) rm = fmaxf(fmaxf(rm, p1[i]), p0[i + 1]);
;             rm = fmaxf(rm, p1[15]);
;             { const auto rr_ = __builtin_amdgcn_permlane32_swap(__float_as_uint(rm), __float_as_uint(rm), false, false);
;               rm = fmaxf(__uint_as_float(rr_[0]), __uint_as_float(rr_[1])); }
;             const bool grow = rm > mloc + THR;
;             if (__any(grow)) {
;                 const float mnew = grow ? rm : mloc; const float al = __builtin_amdgcn_exp2f(mloc - mnew);
;                 lsum *= al; mref = grow ? (mnew + cqt) : mref; mloc = mnew;
;                 if (h == 0) wsf[r] = al;
.Lfp_loop:
	s_mov_b32 s100, 0
	s_add_i32 s2, s87, 3
	s_cmp_ge_u32 s2, s1
	s_cselect_b64 s[2:3], -1, 0
	s_cbranch_scc1 .Lfp_noK
	s_mul_i32 s4, s86, 0xa100
	s_add_i32 s5, s33, s4
	s_mov_b32 s88, m0
	s_mov_b32 m0, s5
	s_nop 0
	global_load_lds_dwordx4 v[102:103], off
	s_mov_b32 m0, s88
	s_andn2_b64 vcc, exec, s[96:97]
	s_cbranch_vccnz .Lfp_noK
	s_addk_i32 s4, 0x4000
	v_lshl_add_u64 v[130:131], s[84:85], 2, v[98:99]
	s_mov_b32 s88, m0
	s_mov_b32 m0, s4
	s_nop 0
	global_load_lds_dword v[130:131], off
	s_mov_b32 m0, s88
.Lfp_noK:
	s_cmp_eq_u32 s87, 0
	s_cbranch_scc1 .Lfp_noV
	s_add_i32 s4, s87, 1
	s_cmp_ge_u32 s4, s1
	s_cbranch_scc1 .Lfp_noV
	s_add_i32 s4, s86, 1
	s_cmp_lg_u32 s86, 2
	s_cselect_b32 s4, s4, 0
	s_mul_i32 s4, s4, 0xa100
	s_add_i32 s5, s9, s4
	s_mov_b32 s88, m0
	s_mov_b32 m0, s5
	s_nop 0
	global_load_lds_dwordx4 v[100:101], off
	s_mov_b32 m0, s88
.Lfp_noV:
	s_add_i32 s4, s11, 1
	s_cmp_gt_u32 s87, s4
	s_cbranch_scc1 .Lfp_end
	s_cmp_eq_u32 s87, s4
	s_cbranch_scc1 .Lfp_pvonly
	s_cmp_eq_u32 s87, s11
	s_cbranch_scc1 .Lfp_lastsel
	s_cmp_eq_u32 s87, 0
	s_cbranch_scc1 .Lfp_first
	s_branch .Lfp_full
.Lfp_lastsel:
	s_cmp_eq_u32 s87, 0
	s_cbranch_scc1 .Lfp_last0
	s_branch .Lfp_last
.Lfp_full:
	s_add_i32 s4, s86, 2
	s_cmp_gt_u32 s4, 2
	s_cselect_b32 s5, 3, 0
	s_sub_i32 s4, s4, s5
	s_mul_i32 s4, s4, 0xa100
	v_add3_u32 v210, s4, v149, v1
	v_add_u32_e32 v210, v210, v154
	ds_read_b64_tr_b16 v[82:83], v210 offset:8192
	ds_read_b64_tr_b16 v[84:85], v210 offset:8704
	ds_read_b64_tr_b16 v[86:87], v210 offset:9216
	ds_read_b64_tr_b16 v[88:89], v210 offset:9728
	ds_read_b64_tr_b16 v[90:91], v210 offset:10240
	ds_read_b64_tr_b16 v[92:93], v210 offset:10752
	ds_read_b64_tr_b16 v[94:95], v210 offset:11264
	ds_read_b64_tr_b16 v[96:97], v210 offset:11776
	ds_read_b64_tr_b16 v[112:113], v210 offset:12288
	ds_read_b64_tr_b16 v[114:115], v210 offset:12800
	ds_read_b64_tr_b16 v[116:117], v210 offset:13312
	ds_read_b64_tr_b16 v[118:119], v210 offset:13824
	ds_read_b64_tr_b16 v[120:121], v210 offset:14336
	ds_read_b64_tr_b16 v[122:123], v210 offset:14848
	ds_read_b64_tr_b16 v[124:125], v210 offset:15360
	ds_read_b64_tr_b16 v[126:127], v210 offset:15872
	s_add_i32 s6, s86, 1
	s_cmp_lg_u32 s86, 2
	s_cselect_b32 s6, s6, 0
	s_mul_i32 s6, s6, 0xa100
	v_readlane_b32 s5, v107, s87
	v_max3_f32 v216, v50, v51, v52
	v_max3_f32 v217, v34, v35, v36
	v_max3_f32 v216, v216, v53, v54
	v_max3_f32 v217, v217, v37, v38
	v_max3_f32 v216, v216, v55, v56
	v_max3_f32 v217, v217, v39, v40
	s_waitcnt lgkmcnt(14)
	v_mfma_f32_32x32x16_bf16 v[2:17], v[192:195], v[82:85], v[2:17]
	v_max3_f32 v216, v216, v57, v58
	v_max3_f32 v217, v217, v41, v42
	v_max3_f32 v216, v216, v59, v60
	v_max3_f32 v217, v217, v43, v44
	v_max3_f32 v216, v216, v61, v62
	v_max3_f32 v217, v217, v45, v46
	s_waitcnt lgkmcnt(12)
	v_mfma_f32_32x32x16_bf16 v[2:17], v[198:201], v[86:89], v[2:17]
	v_max3_f32 v216, v216, v63, v64
	v_max3_f32 v217, v217, v47, v48
	v_max_f32_e32 v216, v216, v65
	v_max_f32_e32 v217, v217, v49
	v_max_f32_e32 v216, v216, v217
	v_subrev_f32_e32 v231, s5, v109
	s_waitcnt lgkmcnt(10)
	v_mfma_f32_32x32x16_bf16 v[2:17], v[202:205], v[90:93], v[2:17]
	v_mov_b32_e32 v217, v216
	v_sub_f32_e32 v248, v111, v231
	v_add_f32_e32 v250, 0x40c00000, v248
	v_permlane32_swap_b32_e32 v216, v217
	v_max_f32_e32 v217, v217, v217
	s_waitcnt lgkmcnt(8)
	v_mfma_f32_32x32x16_bf16 v[2:17], v[206:209], v[94:97], v[2:17]
	v_max_f32_e32 v216, v216, v216
	v_max_f32_e32 v216, v216, v217
	v_cmp_gt_f32_e32 vcc, v216, v250
	s_cbranch_vccz .Lfp_ng_full
	s_nop 0
	v_cndmask_b32_e32 v249, v248, v216, vcc
	v_sub_f32_e32 v250, v248, v249
	v_exp_f32_e32 v250, v250
	v_add_f32_e32 v231, v231, v216
	v_cndmask_b32_e32 v111, v111, v231, vcc
	s_and_saveexec_b64 s[4:5], s[12:13]
	ds_write_b32 v108, v250
	s_or_b64 exec, exec, s[4:5]
	s_waitcnt lgkmcnt(0)
	v_mul_f32_e32 v110, v110, v250
	s_mov_b32 s100, 1
	s_branch .Lfp_gd_full
.Lfp_ng_full:
	v_mov_b32_e32 v249, v248
; #define LAS __attribute__((address_space(3)))
; template <int DQK, int DV, bool FOX> ...
;     ...
;             float ps = 0.f; f32x2v ps2 = {0.f, 0.f};
; #pragma unroll
;             for (int i = 0; i < 16; i += 2) { const f32x2v ml = (f32x2v){mloc, mloc};
;                 const f32x2v a0 = (f32x2v){p0[i], p0[i + 1]} - ml, a1 = (f32x2v){p1[i], p1[i + 1]} - ml;
;                 f32x2v e0, e1; e0.x = __builtin_amdgcn_exp2f(a0.x); e0.y = __builtin_amdgcn_exp2f(a0.y); e1.x = __builtin_amdgcn_exp2f(a1.x); e1.y = __builtin_amdgcn_exp2f(a1.y);
;                 p0[i] = e0.x; p0[i + 1] = e0.y; p1[i] = e1.x; p1[i + 1] = e1.y; ps2 += e0 + e1; }
;             ps = ps2.x + ps2.y;
;             lsum += ps;
;             bf16x8 pa[4];
;             { u32x4 t0, t1, t2, t3;
;               t0.x = pg8::cvt_pk_bf16(p0[0], p0[1]); t0.y = pg8::cvt_pk_bf16(p0[2], p0[3]); t0.z = pg8::cvt_pk_bf16(p0[4], p0[5]); t0.w = pg8::cvt_pk_bf16(p0[6], p0[7]);
;               t1.x = pg8::cvt_pk_bf16(p0[8], p0[9]); t1.y = pg8::cvt_pk_bf16(p0[10], p0[11]); t1.z = pg8::cvt_pk_bf16(p0[12], p0[13]); t1.w = pg8::cvt_pk_bf16(p0[14], p0[15]);
;               t2.x = pg8::cvt_pk_bf16(p1[0], p1[1]); t2.y = pg8::cvt_pk_bf16(p1[2], p1[3]); t2.z = pg8::cvt_pk_bf16(p1[4], p1[5]); t2.w = pg8::cvt_pk_bf16(p1[6], p1[7]);
;               t3.x = pg8::cvt_pk_bf16(p1[8], p1[9]); t3.y = pg8::cvt_pk_bf16(p1[10], p1[11]); t3.z = pg8::cvt_pk_bf16(p1[12], p1[13]); t3.w = pg8::cvt_pk_bf16(p1[14], p1[15]);
;               pa[0] = __builtin_bit_cast(bf16x8, t0); pa[1] = __builtin_bit_cast(bf16x8, t1); pa[2] = __builtin_bit_cast(bf16x8, t2); pa[3] = __builtin_bit_cast(bf16x8, t3); }
; #pragma unroll
;             for (int cb = 0; cb < NCB; ++cb) { s16x4 lo[4], hi[4];
; #pragma unroll
;                 for (int ks = 0; ks < 4; ++ks) {
;                     if (FOX && cb == 0) { lo[ks] = vlo0[ks]; hi[ks] = vhi0[ks]; }
;                     else {
;                     lo[ks] = __builtin_bit_cast(s16x4, __builtin_amdgcn_ds_read_tr16_b64_v4i16((LAS s16x4*)(b + vread0 + cb * 4096 + ks * 1024)));
;                     hi[ks] = __builtin_bit_cast(s16x4, __builtin_amdgcn_ds_read_tr16_b64_v4i16((LAS s16x4*)(b + vread0 + cb * 4096 + ks * 1024 + 512))); } }
;                 __builtin_amdgcn_sched_barrier(0);
; #pragma unroll
.Lfp_gd_full:
	v_sub_f32_e32 v130, v50, v249
	v_sub_f32_e32 v131, v51, v249
	v_sub_f32_e32 v132, v52, v249
	v_sub_f32_e32 v133, v53, v249
	v_exp_f32_e32 v130, v130
	v_exp_f32_e32 v131, v131
	v_exp_f32_e32 v132, v132
	v_exp_f32_e32 v133, v133
	s_waitcnt lgkmcnt(6)
	v_mfma_f32_32x32x16_bf16 v[18:33], v[192:195], v[112:115], v[18:33]
	v_sub_f32_e32 v134, v54, v249
	v_sub_f32_e32 v135, v55, v249
	v_sub_f32_e32 v136, v56, v249
	v_sub_f32_e32 v137, v57, v249
	v_exp_f32_e32 v134, v134
	v_exp_f32_e32 v135, v135
	v_exp_f32_e32 v136, v136
	v_exp_f32_e32 v137, v137
	s_waitcnt lgkmcnt(4)
	v_mfma_f32_32x32x16_bf16 v[18:33], v[198:201], v[116:119], v[18:33]
	v_sub_f32_e32 v138, v58, v249
	v_sub_f32_e32 v139, v59, v249
	v_sub_f32_e32 v140, v60, v249
	v_sub_f32_e32 v141, v61, v249
	v_exp_f32_e32 v138, v138
	v_exp_f32_e32 v139, v139
	v_exp_f32_e32 v140, v140
	v_exp_f32_e32 v141, v141
	s_waitcnt lgkmcnt(2)
	v_mfma_f32_32x32x16_bf16 v[18:33], v[202:205], v[120:123], v[18:33]
	v_sub_f32_e32 v142, v62, v249
	v_sub_f32_e32 v143, v63, v249
	v_sub_f32_e32 v144, v64, v249
	v_sub_f32_e32 v145, v65, v249
	v_exp_f32_e32 v142, v142
	v_exp_f32_e32 v143, v143
	v_exp_f32_e32 v144, v144
	v_exp_f32_e32 v145, v145
	s_waitcnt lgkmcnt(0)
	v_mfma_f32_32x32x16_bf16 v[18:33], v[206:209], v[124:127], v[18:33]
	v_lshl_add_u32 v214, v147, 2, s6
	ds_read_b128 v[50:53], v214 offset:16384
	ds_read_b128 v[54:57], v214 offset:16416
	ds_read_b128 v[58:61], v214 offset:16448
	ds_read_b128 v[62:65], v214 offset:16480
	v_lshlrev_b32_e32 v215, 7, v146
	v_add_u32_e32 v215, s6, v215
	v_add_u32_e32 v86, v215, v197
	v_add_u32_e32 v94, v215, v211
	v_add_u32_e32 v116, v215, v212
	v_add_u32_e32 v215, v215, v213
	ds_read_b128 v[82:85], v86
	ds_read_b128 v[90:93], v94
	ds_read_b128 v[112:115], v116
	ds_read_b128 v[120:123], v215
	ds_read_b128 v[86:89], v86 offset:4096
	ds_read_b128 v[94:97], v94 offset:4096
	ds_read_b128 v[116:119], v116 offset:4096
	ds_read_b128 v[124:127], v215 offset:4096
	v_sub_f32_e32 v232, v34, v249
	v_sub_f32_e32 v233, v35, v249
	v_sub_f32_e32 v234, v36, v249
	v_sub_f32_e32 v235, v37, v249
	v_exp_f32_e32 v232, v232
	v_exp_f32_e32 v233, v233
	v_exp_f32_e32 v234, v234
	v_exp_f32_e32 v235, v235
	v_sub_f32_e32 v236, v38, v249
	v_sub_f32_e32 v237, v39, v249
	v_sub_f32_e32 v238, v40, v249
	v_sub_f32_e32 v239, v41, v249
	v_exp_f32_e32 v236, v236
	v_exp_f32_e32 v237, v237
	s_waitcnt lgkmcnt(7)
	v_mfma_f32_32x32x16_bf16 v[50:65], v[82:85], v[66:69], v[50:65]
	v_exp_f32_e32 v238, v238
	v_exp_f32_e32 v239, v239
	v_sub_f32_e32 v240, v42, v249
	v_sub_f32_e32 v241, v43, v249
	v_sub_f32_e32 v242, v44, v249
	v_sub_f32_e32 v243, v45, v249
	s_waitcnt lgkmcnt(6)
	v_mfma_f32_32x32x16_bf16 v[50:65], v[90:93], v[70:73], v[50:65]
	v_exp_f32_e32 v240, v240
	v_exp_f32_e32 v241, v241
	v_exp_f32_e32 v242, v242
	v_exp_f32_e32 v243, v243
	v_sub_f32_e32 v244, v46, v249
	v_sub_f32_e32 v245, v47, v249
	s_waitcnt lgkmcnt(5)
	v_mfma_f32_32x32x16_bf16 v[50:65], v[112:115], v[74:77], v[50:65]
	v_sub_f32_e32 v246, v48, v249
	v_sub_f32_e32 v247, v49, v249
	v_exp_f32_e32 v244, v244
	v_exp_f32_e32 v245, v245
	v_exp_f32_e32 v246, v246
	v_exp_f32_e32 v247, v247
	s_waitcnt lgkmcnt(4)
	v_mfma_f32_32x32x16_bf16 v[50:65], v[120:123], v[78:81], v[50:65]
	ds_read_b128 v[34:37], v214 offset:16512
	ds_read_b128 v[38:41], v214 offset:16544
	ds_read_b128 v[42:45], v214 offset:16576
	ds_read_b128 v[46:49], v214 offset:16608
	v_add_f32_e32 v251, v130, v131
	v_add_f32_e32 v252, v138, v139
	v_add_f32_e32 v253, v232, v233
	v_add_f32_e32 v254, v240, v241
	v_add_f32_e32 v251, v251, v132
	v_add_f32_e32 v252, v252, v140
	v_add_f32_e32 v253, v253, v234
	v_add_f32_e32 v254, v254, v242
	v_add_f32_e32 v251, v251, v133
	v_add_f32_e32 v252, v252, v141
	v_add_f32_e32 v253, v253, v235
	v_add_f32_e32 v254, v254, v243
	s_waitcnt lgkmcnt(0)
	v_mfma_f32_32x32x16_bf16 v[34:49], v[86:89], v[66:69], v[34:49]
	v_add_f32_e32 v251, v251, v134
	v_add_f32_e32 v252, v252, v142
	v_add_f32_e32 v253, v253, v236
	v_add_f32_e32 v254, v254, v244
	v_add_f32_e32 v251, v251, v135
	v_add_f32_e32 v252, v252, v143
	v_add_f32_e32 v253, v253, v237
	v_add_f32_e32 v254, v254, v245
	v_add_f32_e32 v251, v251, v136
	v_add_f32_e32 v252, v252, v144
	v_mfma_f32_32x32x16_bf16 v[34:49], v[94:97], v[70:73], v[34:49]
	v_add_f32_e32 v253, v253, v238
	v_add_f32_e32 v254, v254, v246
	v_add_f32_e32 v251, v251, v137
	v_add_f32_e32 v252, v252, v145
	v_add_f32_e32 v253, v253, v239
	v_add_f32_e32 v254, v254, v247
	v_cvt_pk_bf16_f32 v192, v130, v131
	v_cvt_pk_bf16_f32 v193, v132, v133
	v_cvt_pk_bf16_f32 v194, v134, v135
	v_cvt_pk_bf16_f32 v195, v136, v137
	v_mfma_f32_32x32x16_bf16 v[34:49], v[116:119], v[74:77], v[34:49]
	v_add_f32_e32 v251, v251, v252
	v_cvt_pk_bf16_f32 v198, v138, v139
	v_cvt_pk_bf16_f32 v199, v140, v141
	v_cvt_pk_bf16_f32 v200, v142, v143
	v_cvt_pk_bf16_f32 v201, v144, v145
	v_add_f32_e32 v253, v253, v254
	v_cvt_pk_bf16_f32 v202, v232, v233
	v_cvt_pk_bf16_f32 v203, v234, v235
	v_cvt_pk_bf16_f32 v204, v236, v237
	v_cvt_pk_bf16_f32 v205, v238, v239
	v_mfma_f32_32x32x16_bf16 v[34:49], v[124:127], v[78:81], v[34:49]
	v_add_f32_e32 v251, v251, v253
	v_cvt_pk_bf16_f32 v206, v240, v241
	v_cvt_pk_bf16_f32 v207, v242, v243
	v_cvt_pk_bf16_f32 v208, v244, v245
	v_cvt_pk_bf16_f32 v209, v246, v247
	v_add_f32_e32 v110, v110, v251
	s_branch .Lfp_end
.Lfp_first:
	s_add_i32 s6, s86, 1
	s_cmp_lg_u32 s86, 2
	s_cselect_b32 s6, s6, 0
	s_mul_i32 s6, s6, 0xa100
	v_readlane_b32 s5, v107, s87
	v_max3_f32 v216, v50, v51, v52
	v_max3_f32 v217, v34, v35, v36
	v_max3_f32 v216, v216, v53, v54
	v_max3_f32 v217, v217, v37, v38
	v_max3_f32 v216, v216, v55, v56
	v_max3_f32 v217, v217, v39, v40
	v_max3_f32 v216, v216, v57, v58
	v_max3_f32 v217, v217, v41, v42
	v_max3_f32 v216, v216, v59, v60
	v_max3_f32 v217, v217, v43, v44
	v_max3_f32 v216, v216, v61, v62
	v_max3_f32 v217, v217, v45, v46
	v_max3_f32 v216, v216, v63, v64
	v_max3_f32 v217, v217, v47, v48
	v_max_f32_e32 v216, v216, v65
	v_max_f32_e32 v217, v217, v49
	v_max_f32_e32 v216, v216, v217
	v_subrev_f32_e32 v231, s5, v109
	v_mov_b32_e32 v217, v216
	v_sub_f32_e32 v248, v111, v231
	v_add_f32_e32 v250, 0x40c00000, v248
	v_permlane32_swap_b32_e32 v216, v217
	v_max_f32_e32 v217, v217, v217
	v_max_f32_e32 v216, v216, v216
	v_max_f32_e32 v216, v216, v217
	v_cmp_gt_f32_e32 vcc, v216, v250
	s_cbranch_vccz .Lfp_ng_first
	s_nop 0
	v_cndmask_b32_e32 v249, v248, v216, vcc
	v_sub_f32_e32 v250, v248, v249
	v_exp_f32_e32 v250, v250
	v_add_f32_e32 v231, v231, v216
	v_cndmask_b32_e32 v111, v111, v231, vcc
	s_and_saveexec_b64 s[4:5], s[12:13]
	ds_write_b32 v108, v250
	s_or_b64 exec, exec, s[4:5]
	s_waitcnt lgkmcnt(0)
	v_mul_f32_e32 v110, v110, v250
	s_mov_b32 s100, 1
	s_branch .Lfp_gd_first

; #define LAS __attribute__((address_space(3)))
; template <int DQK, int DV, bool FOX> ...
;     ...
;             if (FOX) {
;                 const LAS float* ck = (const LAS float*)(b + KT_BYTES + VT_BYTES);
; #pragma unroll
;                 for (int g = 0; g < 4; ++g) { const f32x4 c0 = *(const LAS f32x4*)(ck + 8 * g + 4 * h), c1 = *(const LAS f32x4*)(ck + 32 + 8 * g + 4 * h);
; #pragma unroll
;                     for (int e = 0; e < 4; ++e) { p0[4 * g + e] = c0[e]; p1[4 * g + e] = c1[e]; } }
;             } else {
; #pragma unroll
;             for (int i = 0; i < 16; ++i) { p0[i] = 0.f; p1[i] = 0.f; }
;             }
;             {
;                 constexpr int GB = FOX ? 4 : 3;
; #pragma unroll
;                 for (int g0 = 0; g0 < ND0; g0 += GB) { bf16x8 ka[GB], kb[GB];
; #pragma unroll
;     ...
;             float ps = 0.f; f32x2v ps2 = {0.f, 0.f};
; #pragma unroll
;             for (int i = 0; i < 16; i += 2) { const f32x2v ml = (f32x2v){mloc, mloc};
;                 const f32x2v a0 = (f32x2v){p0[i], p0[i + 1]} - ml, a1 = (f32x2v){p1[i], p1[i + 1]} - ml;
;                 f32x2v e0, e1; e0.x = __builtin_amdgcn_exp2f(a0.x); e0.y = __builtin_amdgcn_exp2f(a0.y); e1.x = __builtin_amdgcn_exp2f(a1.x); e1.y = __builtin_amdgcn_exp2f(a1.y);
;                 p0[i] = e0.x; p0[i + 1] = e0.y; p1[i] = e1.x; p1[i + 1] = e1.y; ps2 += e0 + e1; }
;             ps = ps2.x + ps2.y;
;             lsum += ps;
;             bf16x8 pa[4];
;             { u32x4 t0, t1, t2, t3;
;               t0.x = pg8::cvt_pk_bf16(p0[0], p0[1]); t0.y = pg8::cvt_pk_bf16(p0[2], p0[3]); t0.z = pg8::cvt_pk_bf16(p0[4], p0[5]); t0.w = pg8::cvt_pk_bf16(p0[6], p0[7]);
;               t1.x = pg8::cvt_pk_bf16(p0[8], p0[9]); t1.y = pg8::cvt_pk_bf16(p0[10], p0[11]); t1.z = pg8::cvt_pk_bf16(p0[12], p0[13]); t1.w = pg8::cvt_pk_bf16(p0[14], p0[15]);
;               t2.x = pg8::cvt_pk_bf16(p1[0], p1[1]); t2.y = pg8::cvt_pk_bf16(p1[2], p1[3]); t2.z = pg8::cvt_pk_bf16(p1[4], p1[5]); t2.w = pg8::cvt_pk_bf16(p1[6], p1[7]);
;               t3.x = pg8::cvt_pk_bf16(p1[8], p1[9]); t3.y = pg8::cvt_pk_bf16(p1[10], p1[11]); t3.z = pg8::cvt_pk_bf16(p1[12], p1[13]); t3.w = pg8::cvt_pk_bf16(p1[14], p1[15]);
;               pa[0] = __builtin_bit_cast(bf16x8, t0); pa[1] = __builtin_bit_cast(bf16x8, t1); pa[2] = __builtin_bit_cast(bf16x8, t2); pa[3] = __builtin_bit_cast(bf16x8, t3); }
.Lfp_gd_first:
	v_sub_f32_e32 v130, v50, v249
	v_sub_f32_e32 v131, v51, v249
	v_sub_f32_e32 v132, v52, v249
	v_sub_f32_e32 v133, v53, v249
	v_exp_f32_e32 v130, v130
	v_exp_f32_e32 v131, v131
	v_exp_f32_e32 v132, v132
	v_exp_f32_e32 v133, v133
	v_sub_f32_e32 v134, v54, v249
	v_sub_f32_e32 v135, v55, v249
	v_sub_f32_e32 v136, v56, v249
	v_sub_f32_e32 v137, v57, v249
	v_exp_f32_e32 v134, v134
	v_exp_f32_e32 v135, v135
	v_exp_f32_e32 v136, v136
	v_exp_f32_e32 v137, v137
	v_sub_f32_e32 v138, v58, v249
	v_sub_f32_e32 v139, v59, v249
	v_sub_f32_e32 v140, v60, v249
	v_sub_f32_e32 v141, v61, v249
	v_exp_f32_e32 v138, v138
	v_exp_f32_e32 v139, v139
	v_exp_f32_e32 v140, v140
	v_exp_f32_e32 v141, v141
	v_sub_f32_e32 v142, v62, v249
	v_sub_f32_e32 v143, v63, v249
	v_sub_f32_e32 v144, v64, v249
	v_sub_f32_e32 v145, v65, v249
	v_exp_f32_e32 v142, v142
	v_exp_f32_e32 v143, v143
	v_exp_f32_e32 v144, v144
	v_exp_f32_e32 v145, v145
	v_lshl_add_u32 v214, v147, 2, s6
	ds_read_b128 v[50:53], v214 offset:16384
	ds_read_b128 v[54:57], v214 offset:16416
	ds_read_b128 v[58:61], v214 offset:16448
	ds_read_b128 v[62:65], v214 offset:16480
	v_lshlrev_b32_e32 v215, 7, v146
	v_add_u32_e32 v215, s6, v215
	v_add_u32_e32 v86, v215, v197
	v_add_u32_e32 v94, v215, v211
	v_add_u32_e32 v116, v215, v212
	v_add_u32_e32 v215, v215, v213
	ds_read_b128 v[82:85], v86
	ds_read_b128 v[90:93], v94
	ds_read_b128 v[112:115], v116
	ds_read_b128 v[120:123], v215
	ds_read_b128 v[86:89], v86 offset:4096
	ds_read_b128 v[94:97], v94 offset:4096
	ds_read_b128 v[116:119], v116 offset:4096
	ds_read_b128 v[124:127], v215 offset:4096
	v_sub_f32_e32 v232, v34, v249
	v_sub_f32_e32 v233, v35, v249
	v_sub_f32_e32 v234, v36, v249
	v_sub_f32_e32 v235, v37, v249
	v_exp_f32_e32 v232, v232
	v_exp_f32_e32 v233, v233
	v_exp_f32_e32 v234, v234
	v_exp_f32_e32 v235, v235
	v_sub_f32_e32 v236, v38, v249
	v_sub_f32_e32 v237, v39, v249
	v_sub_f32_e32 v238, v40, v249
	v_sub_f32_e32 v239, v41, v249
	v_exp_f32_e32 v236, v236
	v_exp_f32_e32 v237, v237
	s_waitcnt lgkmcnt(7)
	v_mfma_f32_32x32x16_bf16 v[50:65], v[82:85], v[66:69], v[50:65]
	v_exp_f32_e32 v238, v238
	v_exp_f32_e32 v239, v239
	v_sub_f32_e32 v240, v42, v249
	v_sub_f32_e32 v241, v43, v249
	v_sub_f32_e32 v242, v44, v249
	v_sub_f32_e32 v243, v45, v249
	s_waitcnt lgkmcnt(6)
	v_mfma_f32_32x32x16_bf16 v[50:65], v[90:93], v[70:73], v[50:65]
	v_exp_f32_e32 v240, v240
	v_exp_f32_e32 v241, v241
	v_exp_f32_e32 v242, v242
	v_exp_f32_e32 v243, v243
	v_sub_f32_e32 v244, v46, v249
	v_sub_f32_e32 v245, v47, v249
	s_waitcnt lgkmcnt(5)
	v_mfma_f32_32x32x16_bf16 v[50:65], v[112:115], v[74:77], v[50:65]
	v_sub_f32_e32 v246, v48, v249
	v_sub_f32_e32 v247, v49, v249
	v_exp_f32_e32 v244, v244
	v_exp_f32_e32 v245, v245
	v_exp_f32_e32 v246, v246
	v_exp_f32_e32 v247, v247
	s_waitcnt lgkmcnt(4)
	v_mfma_f32_32x32x16_bf16 v[50:65], v[120:123], v[78:81], v[50:65]
	ds_read_b128 v[34:37], v214 offset:16512
	ds_read_b128 v[38:41], v214 offset:16544
	ds_read_b128 v[42:45], v214 offset:16576
	ds_read_b128 v[46:49], v214 offset:16608
	v_add_f32_e32 v251, v130, v131
	v_add_f32_e32 v252, v138, v139
	v_add_f32_e32 v253, v232, v233
	v_add_f32_e32 v254, v240, v241
	v_add_f32_e32 v251, v251, v132
	v_add_f32_e32 v252, v252, v140
	v_add_f32_e32 v253, v253, v234
	v_add_f32_e32 v254, v254, v242
	v_add_f32_e32 v251, v251, v133
	v_add_f32_e32 v252, v252, v141
	v_add_f32_e32 v253, v253, v235
	v_add_f32_e32 v254, v254, v243
	s_waitcnt lgkmcnt(0)
	v_mfma_f32_32x32x16_bf16 v[34:49], v[86:89], v[66:69], v[34:49]
	v_add_f32_e32 v251, v251, v134
	v_add_f32_e32 v252, v252, v142
	v_add_f32_e32 v253, v253, v236
	v_add_f32_e32 v254, v254, v244
	v_add_f32_e32 v251, v251, v135
	v_add_f32_e32 v252, v252, v143
	v_add_f32_e32 v253, v253, v237
	v_add_f32_e32 v254, v254, v245
	v_add_f32_e32 v251, v251, v136
	v_add_f32_e32 v252, v252, v144
	v_mfma_f32_32x32x16_bf16 v[34:49], v[94:97], v[70:73], v[34:49]
	v_add_f32_e32 v253, v253, v238
	v_add_f32_e32 v254, v254, v246
	v_add_f32_e32 v251, v251, v137
	v_add_f32_e32 v252, v252, v145
	v_add_f32_e32 v253, v253, v239
	v_add_f32_e32 v254, v254, v247
	v_cvt_pk_bf16_f32 v192, v130, v131
	v_cvt_pk_bf16_f32 v193, v132, v133
	v_cvt_pk_bf16_f32 v194, v134, v135
	v_cvt_pk_bf16_f32 v195, v136, v137
	v_mfma_f32_32x32x16_bf16 v[34:49], v[116:119], v[74:77], v[34:49]
	v_add_f32_e32 v251, v251, v252
	v_cvt_pk_bf16_f32 v198, v138, v139
	v_cvt_pk_bf16_f32 v199, v140, v141
	v_cvt_pk_bf16_f32 v200, v142, v143
	v_cvt_pk_bf16_f32 v201, v144, v145
	v_add_f32_e32 v253, v253, v254
	v_cvt_pk_bf16_f32 v202, v232, v233
	v_cvt_pk_bf16_f32 v203, v234, v235
	v_cvt_pk_bf16_f32 v204, v236, v237
	v_cvt_pk_bf16_f32 v205, v238, v239
	v_mfma_f32_32x32x16_bf16 v[34:49], v[124:127], v[78:81], v[34:49]
	v_add_f32_e32 v251, v251, v253
	v_cvt_pk_bf16_f32 v206, v240, v241
	v_cvt_pk_bf16_f32 v207, v242, v243
	v_cvt_pk_bf16_f32 v208, v244, v245
	v_cvt_pk_bf16_f32 v209, v246, v247
	v_add_f32_e32 v110, v110, v251
	s_branch .Lfp_end
; __device__ __forceinline__ int crow(int r, int hi) { return (r & 3) + 8 * (r >> 2) + 4 * hi; }
; template <int DQK, int DV, bool FOX> ...
;     ...
;                 if (t == ntw - 1) { const int qrel = 32 * (w & 1) + r;
; #pragma unroll
;                     for (int i = 0; i < 16; ++i) { const int kv = crow(i, h); if (kv > qrel) p0[i] = -INFINITY; if (kv + 32 > qrel) p1[i] = -INFINITY; } }
;             }
;             float rm = fmaxf(fmaxf(p0[0], p1[0]), p0[1]);
; #pragma unroll
;             for (int i = 1; i < 15; ++i) rm = fmaxf(fmaxf(rm, p1[i]), p0[i + 1]);
;             rm = fmaxf(rm, p1[15]);
;             { const auto rr_ = __builtin_amdgcn_permlane32_swap(__float_as_uint(rm), __float_as_uint(rm), false, false);
;               rm = fmaxf(__uint_as_float(rr_[0]), __uint_as_float(rr_[1])); }
;             const bool grow = rm > mloc + THR;
;             if (__any(grow)) {
;                 const float mnew = grow ? rm : mloc; const float al = __builtin_amdgcn_exp2f(mloc - mnew);
;                 lsum *= al; mref = grow ? (mnew + cqt) : mref; mloc = mnew;
;                 if (h == 0) wsf[r] = al;
.Lfp_last:
	s_add_i32 s4, s86, 2
	s_cmp_gt_u32 s4, 2
	s_cselect_b32 s5, 3, 0
	s_sub_i32 s4, s4, s5
	s_mul_i32 s4, s4, 0xa100
	v_add3_u32 v210, s4, v149, v1
	v_add_u32_e32 v210, v210, v154
	ds_read_b64_tr_b16 v[82:83], v210 offset:8192
	ds_read_b64_tr_b16 v[84:85], v210 offset:8704
	ds_read_b64_tr_b16 v[86:87], v210 offset:9216
	ds_read_b64_tr_b16 v[88:89], v210 offset:9728
	ds_read_b64_tr_b16 v[90:91], v210 offset:10240
	ds_read_b64_tr_b16 v[92:93], v210 offset:10752
	ds_read_b64_tr_b16 v[94:95], v210 offset:11264
	ds_read_b64_tr_b16 v[96:97], v210 offset:11776
	ds_read_b64_tr_b16 v[112:113], v210 offset:12288
	ds_read_b64_tr_b16 v[114:115], v210 offset:12800
	ds_read_b64_tr_b16 v[116:117], v210 offset:13312
	ds_read_b64_tr_b16 v[118:119], v210 offset:13824
	ds_read_b64_tr_b16 v[120:121], v210 offset:14336
	ds_read_b64_tr_b16 v[122:123], v210 offset:14848
	ds_read_b64_tr_b16 v[124:125], v210 offset:15360
	ds_read_b64_tr_b16 v[126:127], v210 offset:15872
	v_readlane_b32 s5, v107, s87
	v_cndmask_b32_e64 v216, v50, v229, s[14:15]
	v_cndmask_b32_e64 v34, v34, v229, s[16:17]
	v_cndmask_b32_e64 v51, v229, v51, s[18:19]
	v_cndmask_b32_e64 v50, v216, v50, s[18:19]
	v_cndmask_b32_e64 v35, v35, v229, s[20:21]
	v_cndmask_b32_e64 v52, v52, v229, s[22:23]
	v_cndmask_b32_e64 v36, v36, v229, s[24:25]
	v_cndmask_b32_e64 v53, v53, v229, s[26:27]
	v_cndmask_b32_e64 v37, v37, v229, s[28:29]
	v_cndmask_b32_e64 v54, v54, v229, s[30:31]
	s_waitcnt lgkmcnt(14)
	v_mfma_f32_32x32x16_bf16 v[2:17], v[192:195], v[82:85], v[2:17]
	v_cndmask_b32_e64 v38, v38, v229, s[34:35]
	v_cndmask_b32_e64 v55, v55, v229, s[36:37]
	v_cndmask_b32_e64 v39, v39, v229, s[38:39]
	v_cndmask_b32_e64 v56, v56, v229, s[40:41]
	v_cndmask_b32_e64 v40, v40, v229, s[42:43]
	v_cndmask_b32_e64 v57, v57, v229, s[44:45]
	v_cndmask_b32_e64 v41, v41, v229, s[46:47]
	v_cndmask_b32_e64 v58, v58, v229, s[48:49]
	v_cndmask_b32_e64 v42, v42, v229, s[50:51]
	v_cndmask_b32_e64 v59, v59, v229, s[52:53]
	v_cndmask_b32_e64 v43, v43, v229, s[54:55]
	v_cndmask_b32_e64 v60, v60, v229, s[56:57]
	s_waitcnt lgkmcnt(12)
	v_mfma_f32_32x32x16_bf16 v[2:17], v[198:201], v[86:89], v[2:17]
	v_cndmask_b32_e64 v44, v44, v229, s[58:59]
	v_cndmask_b32_e64 v61, v61, v229, s[60:61]
	v_cndmask_b32_e64 v45, v45, v229, s[62:63]
	v_cndmask_b32_e64 v62, v62, v229, s[64:65]
	v_cndmask_b32_e64 v46, v46, v229, s[66:67]
	v_cndmask_b32_e64 v63, v63, v229, s[68:69]
	v_cndmask_b32_e64 v47, v47, v229, s[70:71]
	v_cndmask_b32_e64 v64, v64, v229, s[72:73]
	v_cndmask_b32_e64 v48, v48, v229, s[74:75]
	v_cndmask_b32_e64 v65, v65, v229, s[76:77]
	v_cndmask_b32_e64 v49, v49, v229, s[78:79]
	v_max3_f32 v216, v50, v51, v52
	s_waitcnt lgkmcnt(10)
	v_mfma_f32_32x32x16_bf16 v[2:17], v[202:205], v[90:93], v[2:17]
	v_max3_f32 v217, v34, v35, v36
	v_max3_f32 v216, v216, v53, v54
	v_max3_f32 v217, v217, v37, v38
	v_max3_f32 v216, v216, v55, v56
	v_max3_f32 v217, v217, v39, v40
	v_max3_f32 v216, v216, v57, v58
	v_max3_f32 v217, v217, v41, v42
	v_max3_f32 v216, v216, v59, v60
	v_max3_f32 v217, v217, v43, v44
	v_max3_f32 v216, v216, v61, v62
	v_max3_f32 v217, v217, v45, v46
	v_max3_f32 v216, v216, v63, v64
	s_waitcnt lgkmcnt(8)
	v_mfma_f32_32x32x16_bf16 v[2:17], v[206:209], v[94:97], v[2:17]
	v_max3_f32 v217, v217, v47, v48
	v_max_f32_e32 v216, v216, v65
	v_max_f32_e32 v217, v217, v49
	v_max_f32_e32 v216, v216, v217
	v_subrev_f32_e32 v231, s5, v109
	v_mov_b32_e32 v217, v216
	v_sub_f32_e32 v248, v111, v231
	v_add_f32_e32 v250, 0x40c00000, v248
	v_permlane32_swap_b32_e32 v216, v217
	v_max_f32_e32 v217, v217, v217
	v_max_f32_e32 v216, v216, v216
	v_max_f32_e32 v216, v216, v217
	v_cmp_gt_f32_e32 vcc, v216, v250
	s_cbranch_vccz .Lfp_ng_last
	s_nop 0
	v_cndmask_b32_e32 v249, v248, v216, vcc
	v_sub_f32_e32 v250, v248, v249
	v_exp_f32_e32 v250, v250
	v_add_f32_e32 v231, v231, v216
	v_cndmask_b32_e32 v111, v111, v231, vcc
	s_and_saveexec_b64 s[4:5], s[12:13]
	ds_write_b32 v108, v250
	s_or_b64 exec, exec, s[4:5]
	s_waitcnt lgkmcnt(0)
	v_mul_f32_e32 v110, v110, v250
	s_mov_b32 s100, 1
	s_branch .Lfp_gd_last

; template <int DQK, int DV, bool FOX> ...
;     ...
;                 if (t == ntw - 1) { const int qrel = 32 * (w & 1) + r;
; #pragma unroll
;                     for (int i = 0; i < 16; ++i) { const int kv = crow(i, h); if (kv > qrel) p0[i] = -INFINITY; if (kv + 32 > qrel) p1[i] = -INFINITY; } }
;             }
;             float rm = fmaxf(fmaxf(p0[0], p1[0]), p0[1]);
; #pragma unroll
;             for (int i = 1; i < 15; ++i) rm = fmaxf(fmaxf(rm, p1[i]), p0[i + 1]);
;             rm = fmaxf(rm, p1[15]);
;             { const auto rr_ = __builtin_amdgcn_permlane32_swap(__float_as_uint(rm), __float_as_uint(rm), false, false);
;               rm = fmaxf(__uint_as_float(rr_[0]), __uint_as_float(rr_[1])); }
;             const bool grow = rm > mloc + THR;
;             if (__any(grow)) {
;     ...
;             float ps = 0.f; f32x2v ps2 = {0.f, 0.f};
; #pragma unroll
;             for (int i = 0; i < 16; i += 2) { const f32x2v ml = (f32x2v){mloc, mloc};
;                 const f32x2v a0 = (f32x2v){p0[i], p0[i + 1]} - ml, a1 = (f32x2v){p1[i], p1[i + 1]} - ml;
;                 f32x2v e0, e1; e0.x = __builtin_amdgcn_exp2f(a0.x); e0.y = __builtin_amdgcn_exp2f(a0.y); e1.x = __builtin_amdgcn_exp2f(a1.x); e1.y = __builtin_amdgcn_exp2f(a1.y);
;                 p0[i] = e0.x; p0[i + 1] = e0.y; p1[i] = e1.x; p1[i + 1] = e1.y; ps2 += e0 + e1; }
;             ps = ps2.x + ps2.y;
;             lsum += ps;
;             bf16x8 pa[4];
;             { u32x4 t0, t1, t2, t3;
;               t0.x = pg8::cvt_pk_bf16(p0[0], p0[1]); t0.y = pg8::cvt_pk_bf16(p0[2], p0[3]); t0.z = pg8::cvt_pk_bf16(p0[4], p0[5]); t0.w = pg8::cvt_pk_bf16(p0[6], p0[7]);
;               t1.x = pg8::cvt_pk_bf16(p0[8], p0[9]); t1.y = pg8::cvt_pk_bf16(p0[10], p0[11]); t1.z = pg8::cvt_pk_bf16(p0[12], p0[13]); t1.w = pg8::cvt_pk_bf16(p0[14], p0[15]);
;               t2.x = pg8::cvt_pk_bf16(p1[0], p1[1]); t2.y = pg8::cvt_pk_bf16(p1[2], p1[3]); t2.z = pg8::cvt_pk_bf16(p1[4], p1[5]); t2.w = pg8::cvt_pk_bf16(p1[6], p1[7]);
;               t3.x = pg8::cvt_pk_bf16(p1[8], p1[9]); t3.y = pg8::cvt_pk_bf16(p1[10], p1[11]); t3.z = pg8::cvt_pk_bf16(p1[12], p1[13]); t3.w = pg8::cvt_pk_bf16(p1[14], p1[15]);
;               pa[0] = __builtin_bit_cast(bf16x8, t0); pa[1] = __builtin_bit_cast(bf16x8, t1); pa[2] = __builtin_bit_cast(bf16x8, t2); pa[3] = __builtin_bit_cast(bf16x8, t3); }
.Lfp_gd_last:
	v_sub_f32_e32 v130, v50, v249
	v_sub_f32_e32 v131, v51, v249
	v_sub_f32_e32 v132, v52, v249
	v_sub_f32_e32 v133, v53, v249
	v_exp_f32_e32 v130, v130
	v_exp_f32_e32 v131, v131
	v_exp_f32_e32 v132, v132
	v_exp_f32_e32 v133, v133
	s_waitcnt lgkmcnt(6)
	v_mfma_f32_32x32x16_bf16 v[18:33], v[192:195], v[112:115], v[18:33]
	v_sub_f32_e32 v134, v54, v249
	v_sub_f32_e32 v135, v55, v249
	v_sub_f32_e32 v136, v56, v249
	v_sub_f32_e32 v137, v57, v249
	v_exp_f32_e32 v134, v134
	v_exp_f32_e32 v135, v135
	v_exp_f32_e32 v136, v136
	v_exp_f32_e32 v137, v137
	s_waitcnt lgkmcnt(4)
	v_mfma_f32_32x32x16_bf16 v[18:33], v[198:201], v[116:119], v[18:33]
	v_sub_f32_e32 v138, v58, v249
	v_sub_f32_e32 v139, v59, v249
	v_sub_f32_e32 v140, v60, v249
	v_sub_f32_e32 v141, v61, v249
	v_exp_f32_e32 v138, v138
	v_exp_f32_e32 v139, v139
	v_exp_f32_e32 v140, v140
	v_exp_f32_e32 v141, v141
	s_waitcnt lgkmcnt(2)
	v_mfma_f32_32x32x16_bf16 v[18:33], v[202:205], v[120:123], v[18:33]
	v_sub_f32_e32 v142, v62, v249
	v_sub_f32_e32 v143, v63, v249
	v_sub_f32_e32 v144, v64, v249
	v_sub_f32_e32 v145, v65, v249
	v_exp_f32_e32 v142, v142
	v_exp_f32_e32 v143, v143
	v_exp_f32_e32 v144, v144
	v_exp_f32_e32 v145, v145
	s_waitcnt lgkmcnt(0)
	v_mfma_f32_32x32x16_bf16 v[18:33], v[206:209], v[124:127], v[18:33]
	v_sub_f32_e32 v232, v34, v249
	v_sub_f32_e32 v233, v35, v249
	v_sub_f32_e32 v234, v36, v249
	v_sub_f32_e32 v235, v37, v249
	v_exp_f32_e32 v232, v232
	v_exp_f32_e32 v233, v233
	v_exp_f32_e32 v234, v234
	v_exp_f32_e32 v235, v235
	v_sub_f32_e32 v236, v38, v249
	v_sub_f32_e32 v237, v39, v249
	v_sub_f32_e32 v238, v40, v249
	v_sub_f32_e32 v239, v41, v249
	v_exp_f32_e32 v236, v236
	v_exp_f32_e32 v237, v237
	v_exp_f32_e32 v238, v238
	v_exp_f32_e32 v239, v239
	v_sub_f32_e32 v240, v42, v249
	v_sub_f32_e32 v241, v43, v249
	v_sub_f32_e32 v242, v44, v249
	v_sub_f32_e32 v243, v45, v249
	v_exp_f32_e32 v240, v240
	v_exp_f32_e32 v241, v241
	v_exp_f32_e32 v242, v242
	v_exp_f32_e32 v243, v243
	v_sub_f32_e32 v244, v46, v249
	v_sub_f32_e32 v245, v47, v249
	v_sub_f32_e32 v246, v48, v249
	v_sub_f32_e32 v247, v49, v249
	v_exp_f32_e32 v244, v244
	v_exp_f32_e32 v245, v245
	v_exp_f32_e32 v246, v246
	v_exp_f32_e32 v247, v247
	v_add_f32_e32 v251, v130, v131
	v_add_f32_e32 v252, v138, v139
	v_add_f32_e32 v253, v232, v233
	v_add_f32_e32 v254, v240, v241
	v_add_f32_e32 v251, v251, v132
	v_add_f32_e32 v252, v252, v140
	v_add_f32_e32 v253, v253, v234
	v_add_f32_e32 v254, v254, v242
	v_add_f32_e32 v251, v251, v133
	v_add_f32_e32 v252, v252, v141
	v_add_f32_e32 v253, v253, v235
	v_add_f32_e32 v254, v254, v243
	v_add_f32_e32 v251, v251, v134
	v_add_f32_e32 v252, v252, v142
	v_add_f32_e32 v253, v253, v236
	v_add_f32_e32 v254, v254, v244
	v_add_f32_e32 v251, v251, v135
	v_add_f32_e32 v252, v252, v143
	v_add_f32_e32 v253, v253, v237
	v_add_f32_e32 v254, v254, v245
	v_add_f32_e32 v251, v251, v136
	v_add_f32_e32 v252, v252, v144
	v_add_f32_e32 v253, v253, v238
	v_add_f32_e32 v254, v254, v246
	v_add_f32_e32 v251, v251, v137
	v_add_f32_e32 v252, v252, v145
	v_add_f32_e32 v253, v253, v239
	v_add_f32_e32 v254, v254, v247
	v_cvt_pk_bf16_f32 v192, v130, v131
	v_cvt_pk_bf16_f32 v193, v132, v133
	v_cvt_pk_bf16_f32 v194, v134, v135
	v_cvt_pk_bf16_f32 v195, v136, v137
	v_add_f32_e32 v251, v251, v252
	v_cvt_pk_bf16_f32 v198, v138, v139
	v_cvt_pk_bf16_f32 v199, v140, v141
	v_cvt_pk_bf16_f32 v200, v142, v143
	v_cvt_pk_bf16_f32 v201, v144, v145
	v_add_f32_e32 v253, v253, v254
	v_cvt_pk_bf16_f32 v202, v232, v233
	v_cvt_pk_bf16_f32 v203, v234, v235
	v_cvt_pk_bf16_f32 v204, v236, v237
	v_cvt_pk_bf16_f32 v205, v238, v239
	v_add_f32_e32 v251, v251, v253
	v_cvt_pk_bf16_f32 v206, v240, v241
	v_cvt_pk_bf16_f32 v207, v242, v243
	v_cvt_pk_bf16_f32 v208, v244, v245
	v_cvt_pk_bf16_f32 v209, v246, v247
	v_add_f32_e32 v110, v110, v251
	s_branch .Lfp_end
.Lfp_last0:
	v_readlane_b32 s5, v107, s87
	v_cndmask_b32_e64 v216, v50, v229, s[14:15]
	v_cndmask_b32_e64 v34, v34, v229, s[16:17]
	v_cndmask_b32_e64 v51, v229, v51, s[18:19]
	v_cndmask_b32_e64 v50, v216, v50, s[18:19]
	v_cndmask_b32_e64 v35, v35, v229, s[20:21]
	v_cndmask_b32_e64 v52, v52, v229, s[22:23]
	v_cndmask_b32_e64 v36, v36, v229, s[24:25]
	v_cndmask_b32_e64 v53, v53, v229, s[26:27]
	v_cndmask_b32_e64 v37, v37, v229, s[28:29]
	v_cndmask_b32_e64 v54, v54, v229, s[30:31]
	v_cndmask_b32_e64 v38, v38, v229, s[34:35]
	v_cndmask_b32_e64 v55, v55, v229, s[36:37]
	v_cndmask_b32_e64 v39, v39, v229, s[38:39]
	v_cndmask_b32_e64 v56, v56, v229, s[40:41]
	v_cndmask_b32_e64 v40, v40, v229, s[42:43]
	v_cndmask_b32_e64 v57, v57, v229, s[44:45]
	v_cndmask_b32_e64 v41, v41, v229, s[46:47]
	v_cndmask_b32_e64 v58, v58, v229, s[48:49]
	v_cndmask_b32_e64 v42, v42, v229, s[50:51]
	v_cndmask_b32_e64 v59, v59, v229, s[52:53]
	v_cndmask_b32_e64 v43, v43, v229, s[54:55]
	v_cndmask_b32_e64 v60, v60, v229, s[56:57]
	v_cndmask_b32_e64 v44, v44, v229, s[58:59]
	v_cndmask_b32_e64 v61, v61, v229, s[60:61]
	v_cndmask_b32_e64 v45, v45, v229, s[62:63]
	v_cndmask_b32_e64 v62, v62, v229, s[64:65]
	v_cndmask_b32_e64 v46, v46, v229, s[66:67]
	v_cndmask_b32_e64 v63, v63, v229, s[68:69]
	v_cndmask_b32_e64 v47, v47, v229, s[70:71]
	v_cndmask_b32_e64 v64, v64, v229, s[72:73]
	v_cndmask_b32_e64 v48, v48, v229, s[74:75]
	v_cndmask_b32_e64 v65, v65, v229, s[76:77]
	v_cndmask_b32_e64 v49, v49, v229, s[78:79]
	v_max3_f32 v216, v50, v51, v52
	v_max3_f32 v217, v34, v35, v36
	v_max3_f32 v216, v216, v53, v54
	v_max3_f32 v217, v217, v37, v38
	v_max3_f32 v216, v216, v55, v56
	v_max3_f32 v217, v217, v39, v40
	v_max3_f32 v216, v216, v57, v58
	v_max3_f32 v217, v217, v41, v42
	v_max3_f32 v216, v216, v59, v60
	v_max3_f32 v217, v217, v43, v44
	v_max3_f32 v216, v216, v61, v62
	v_max3_f32 v217, v217, v45, v46
	v_max3_f32 v216, v216, v63, v64
	v_max3_f32 v217, v217, v47, v48
	v_max_f32_e32 v216, v216, v65
	v_max_f32_e32 v217, v217, v49
	v_max_f32_e32 v216, v216, v217
	v_subrev_f32_e32 v231, s5, v109
	v_mov_b32_e32 v217, v216
	v_sub_f32_e32 v248, v111, v231
	v_add_f32_e32 v250, 0x40c00000, v248
	v_permlane32_swap_b32_e32 v216, v217
	v_max_f32_e32 v217, v217, v217
	v_max_f32_e32 v216, v216, v216
	v_max_f32_e32 v216, v216, v217
	v_cmp_gt_f32_e32 vcc, v216, v250
	s_cbranch_vccz .Lfp_ng_last0
	s_nop 0
	v_cndmask_b32_e32 v249, v248, v216, vcc
	v_sub_f32_e32 v250, v248, v249
	v_exp_f32_e32 v250, v250
	v_add_f32_e32 v231, v231, v216
	v_cndmask_b32_e32 v111, v111, v231, vcc
	s_and_saveexec_b64 s[4:5], s[12:13]
	ds_write_b32 v108, v250
	s_or_b64 exec, exec, s[4:5]
	s_waitcnt lgkmcnt(0)
	v_mul_f32_e32 v110, v110, v250
	s_mov_b32 s100, 1
	s_branch .Lfp_gd_last0

; template <int DQK, int DV, bool FOX> ...
;     ...
;                 asm volatile("s_waitcnt lgkmcnt(0)" ::: "memory");
; #pragma unroll
;                 for (int g = 0; g < 4; ++g) { const f32x4 a4 = *(const LAS f32x4*)(wsf + 8 * g + 4 * h);
; #pragma unroll
;                     for (int cb = 0; cb < NCB; ++cb)
; #pragma unroll
;                         for (int e = 0; e < 4; ++e) o[cb][4 * g + e] *= a4[e]; }
;             }
;             float ps = 0.f; f32x2v ps2 = {0.f, 0.f};
; #pragma unroll
;             for (int i = 0; i < 16; i += 2) { const f32x2v ml = (f32x2v){mloc, mloc};
;                 const f32x2v a0 = (f32x2v){p0[i], p0[i + 1]} - ml, a1 = (f32x2v){p1[i], p1[i + 1]} - ml;
;                 f32x2v e0, e1; e0.x = __builtin_amdgcn_exp2f(a0.x); e0.y = __builtin_amdgcn_exp2f(a0.y); e1.x = __builtin_amdgcn_exp2f(a1.x); e1.y = __builtin_amdgcn_exp2f(a1.y);
;                 p0[i] = e0.x; p0[i + 1] = e0.y; p1[i] = e1.x; p1[i + 1] = e1.y; ps2 += e0 + e1; }
;             ps = ps2.x + ps2.y;
;             lsum += ps;
;             bf16x8 pa[4];
;             { u32x4 t0, t1, t2, t3;
;               t0.x = pg8::cvt_pk_bf16(p0[0], p0[1]); t0.y = pg8::cvt_pk_bf16(p0[2], p0[3]); t0.z = pg8::cvt_pk_bf16(p0[4], p0[5]); t0.w = pg8::cvt_pk_bf16(p0[6], p0[7]);
;               t1.x = pg8::cvt_pk_bf16(p0[8], p0[9]); t1.y = pg8::cvt_pk_bf16(p0[10], p0[11]); t1.z = pg8::cvt_pk_bf16(p0[12], p0[13]); t1.w = pg8::cvt_pk_bf16(p0[14], p0[15]);
;               t2.x = pg8::cvt_pk_bf16(p1[0], p1[1]); t2.y = pg8::cvt_pk_bf16(p1[2], p1[3]); t2.z = pg8::cvt_pk_bf16(p1[4], p1[5]); t2.w = pg8::cvt_pk_bf16(p1[6], p1[7]);
;               t3.x = pg8::cvt_pk_bf16(p1[8], p1[9]); t3.y = pg8::cvt_pk_bf16(p1[10], p1[11]); t3.z = pg8::cvt_pk_bf16(p1[12], p1[13]); t3.w = pg8::cvt_pk_bf16(p1[14], p1[15]);
;               pa[0] = __builtin_bit_cast(bf16x8, t0); pa[1] = __builtin_bit_cast(bf16x8, t1); pa[2] = __builtin_bit_cast(bf16x8, t2); pa[3] = __builtin_bit_cast(bf16x8, t3); }
; #pragma unroll
;             for (int cb = 0; cb < NCB; ++cb) { s16x4 lo[4], hi[4];
; #pragma unroll
;                 for (int ks = 0; ks < 4; ++ks) {
;                     if (FOX && cb == 0) { lo[ks] = vlo0[ks]; hi[ks] = vhi0[ks]; }
;                     else {
;                     lo[ks] = __builtin_bit_cast(s16x4, __builtin_amdgcn_ds_read_tr16_b64_v4i16((LAS s16x4*)(b + vread0 + cb * 4096 + ks * 1024)));
.Lfp_gd_last0:
	v_sub_f32_e32 v130, v50, v249
	v_sub_f32_e32 v131, v51, v249
	v_sub_f32_e32 v132, v52, v249
	v_sub_f32_e32 v133, v53, v249
	v_exp_f32_e32 v130, v130
	v_exp_f32_e32 v131, v131
	v_exp_f32_e32 v132, v132
	v_exp_f32_e32 v133, v133
	v_sub_f32_e32 v134, v54, v249
	v_sub_f32_e32 v135, v55, v249
	v_sub_f32_e32 v136, v56, v249
	v_sub_f32_e32 v137, v57, v249
	v_exp_f32_e32 v134, v134
	v_exp_f32_e32 v135, v135
	v_exp_f32_e32 v136, v136
	v_exp_f32_e32 v137, v137
	v_sub_f32_e32 v138, v58, v249
	v_sub_f32_e32 v139, v59, v249
	v_sub_f32_e32 v140, v60, v249
	v_sub_f32_e32 v141, v61, v249
	v_exp_f32_e32 v138, v138
	v_exp_f32_e32 v139, v139
	v_exp_f32_e32 v140, v140
	v_exp_f32_e32 v141, v141
	v_sub_f32_e32 v142, v62, v249
	v_sub_f32_e32 v143, v63, v249
	v_sub_f32_e32 v144, v64, v249
	v_sub_f32_e32 v145, v65, v249
	v_exp_f32_e32 v142, v142
	v_exp_f32_e32 v143, v143
	v_exp_f32_e32 v144, v144
	v_exp_f32_e32 v145, v145
	v_sub_f32_e32 v232, v34, v249
	v_sub_f32_e32 v233, v35, v249
	v_sub_f32_e32 v234, v36, v249
	v_sub_f32_e32 v235, v37, v249
	v_exp_f32_e32 v232, v232
	v_exp_f32_e32 v233, v233
	v_exp_f32_e32 v234, v234
	v_exp_f32_e32 v235, v235
	v_sub_f32_e32 v236, v38, v249
	v_sub_f32_e32 v237, v39, v249
	v_sub_f32_e32 v238, v40, v249
	v_sub_f32_e32 v239, v41, v249
	v_exp_f32_e32 v236, v236
	v_exp_f32_e32 v237, v237
	v_exp_f32_e32 v238, v238
	v_exp_f32_e32 v239, v239
	v_sub_f32_e32 v240, v42, v249
	v_sub_f32_e32 v241, v43, v249
	v_sub_f32_e32 v242, v44, v249
	v_sub_f32_e32 v243, v45, v249
	v_exp_f32_e32 v240, v240
	v_exp_f32_e32 v241, v241
	v_exp_f32_e32 v242, v242
	v_exp_f32_e32 v243, v243
	v_sub_f32_e32 v244, v46, v249
	v_sub_f32_e32 v245, v47, v249
	v_sub_f32_e32 v246, v48, v249
	v_sub_f32_e32 v247, v49, v249
	v_exp_f32_e32 v244, v244
	v_exp_f32_e32 v245, v245
	v_exp_f32_e32 v246, v246
	v_exp_f32_e32 v247, v247
	v_add_f32_e32 v251, v130, v131
	v_add_f32_e32 v252, v138, v139
	v_add_f32_e32 v253, v232, v233
	v_add_f32_e32 v254, v240, v241
	v_add_f32_e32 v251, v251, v132
	v_add_f32_e32 v252, v252, v140
	v_add_f32_e32 v253, v253, v234
	v_add_f32_e32 v254, v254, v242
	v_add_f32_e32 v251, v251, v133
	v_add_f32_e32 v252, v252, v141
	v_add_f32_e32 v253, v253, v235
	v_add_f32_e32 v254, v254, v243
	v_add_f32_e32 v251, v251, v134
	v_add_f32_e32 v252, v252, v142
	v_add_f32_e32 v253, v253, v236
	v_add_f32_e32 v254, v254, v244
	v_add_f32_e32 v251, v251, v135
	v_add_f32_e32 v252, v252, v143
	v_add_f32_e32 v253, v253, v237
	v_add_f32_e32 v254, v254, v245
	v_add_f32_e32 v251, v251, v136
	v_add_f32_e32 v252, v252, v144
	v_add_f32_e32 v253, v253, v238
	v_add_f32_e32 v254, v254, v246
	v_add_f32_e32 v251, v251, v137
	v_add_f32_e32 v252, v252, v145
	v_add_f32_e32 v253, v253, v239
	v_add_f32_e32 v254, v254, v247
	v_cvt_pk_bf16_f32 v192, v130, v131
	v_cvt_pk_bf16_f32 v193, v132, v133
	v_cvt_pk_bf16_f32 v194, v134, v135
	v_cvt_pk_bf16_f32 v195, v136, v137
	v_add_f32_e32 v251, v251, v252
	v_cvt_pk_bf16_f32 v198, v138, v139
	v_cvt_pk_bf16_f32 v199, v140, v141
	v_cvt_pk_bf16_f32 v200, v142, v143
	v_cvt_pk_bf16_f32 v201, v144, v145
	v_add_f32_e32 v253, v253, v254
	v_cvt_pk_bf16_f32 v202, v232, v233
	v_cvt_pk_bf16_f32 v203, v234, v235
	v_cvt_pk_bf16_f32 v204, v236, v237
	v_cvt_pk_bf16_f32 v205, v238, v239
	v_add_f32_e32 v251, v251, v253
	v_cvt_pk_bf16_f32 v206, v240, v241
	v_cvt_pk_bf16_f32 v207, v242, v243
	v_cvt_pk_bf16_f32 v208, v244, v245
	v_cvt_pk_bf16_f32 v209, v246, v247
	v_add_f32_e32 v110, v110, v251
	s_branch .Lfp_end
.Lfp_pvonly:
	s_add_i32 s4, s86, 2
	s_cmp_gt_u32 s4, 2
	s_cselect_b32 s5, 3, 0
	s_sub_i32 s4, s4, s5
	s_mul_i32 s4, s4, 0xa100
	v_add3_u32 v210, s4, v149, v1
	v_add_u32_e32 v210, v210, v154
	ds_read_b64_tr_b16 v[82:83], v210 offset:8192
	ds_read_b64_tr_b16 v[84:85], v210 offset:8704
	ds_read_b64_tr_b16 v[86:87], v210 offset:9216
	ds_read_b64_tr_b16 v[88:89], v210 offset:9728
	ds_read_b64_tr_b16 v[90:91], v210 offset:10240
	ds_read_b64_tr_b16 v[92:93], v210 offset:10752
	ds_read_b64_tr_b16 v[94:95], v210 offset:11264
	ds_read_b64_tr_b16 v[96:97], v210 offset:11776
	ds_read_b64_tr_b16 v[112:113], v210 offset:12288
	ds_read_b64_tr_b16 v[114:115], v210 offset:12800
	ds_read_b64_tr_b16 v[116:117], v210 offset:13312
	ds_read_b64_tr_b16 v[118:119], v210 offset:13824
	ds_read_b64_tr_b16 v[120:121], v210 offset:14336
	ds_read_b64_tr_b16 v[122:123], v210 offset:14848
	ds_read_b64_tr_b16 v[124:125], v210 offset:15360
	ds_read_b64_tr_b16 v[126:127], v210 offset:15872
	s_waitcnt lgkmcnt(14)
	v_mfma_f32_32x32x16_bf16 v[2:17], v[192:195], v[82:85], v[2:17]
	s_waitcnt lgkmcnt(12)
	v_mfma_f32_32x32x16_bf16 v[2:17], v[198:201], v[86:89], v[2:17]
	s_waitcnt lgkmcnt(10)
	v_mfma_f32_32x32x16_bf16 v[2:17], v[202:205], v[90:93], v[2:17]
	s_waitcnt lgkmcnt(8)
	v_mfma_f32_32x32x16_bf16 v[2:17], v[206:209], v[94:97], v[2:17]
	s_waitcnt lgkmcnt(6)
	v_mfma_f32_32x32x16_bf16 v[18:33], v[192:195], v[112:115], v[18:33]
	s_waitcnt lgkmcnt(4)
	v_mfma_f32_32x32x16_bf16 v[18:33], v[198:201], v[116:119], v[18:33]
	s_waitcnt lgkmcnt(2)
	v_mfma_f32_32x32x16_bf16 v[18:33], v[202:205], v[120:123], v[18:33]
	s_waitcnt lgkmcnt(0)
	v_mfma_f32_32x32x16_bf16 v[18:33], v[206:209], v[124:127], v[18:33]
	s_branch .Lfp_end
.Lfp_end:
	s_cmp_lg_u32 s100, 0
	s_cbranch_scc0 .Lfp_nors
	ds_read_b128 v[130:133], v106
	ds_read_b128 v[134:137], v106 offset:32
	ds_read_b128 v[138:141], v106 offset:64
	ds_read_b128 v[142:145], v106 offset:96
	s_waitcnt lgkmcnt(0)
	v_pk_mul_f32 v[2:3], v[2:3], v[130:131]
	v_pk_mul_f32 v[18:19], v[18:19], v[130:131]
	v_pk_mul_f32 v[4:5], v[4:5], v[132:133]
	v_pk_mul_f32 v[20:21], v[20:21], v[132:133]
	v_pk_mul_f32 v[6:7], v[6:7], v[134:135]
	v_pk_mul_f32 v[22:23], v[22:23], v[134:135]
	v_pk_mul_f32 v[8:9], v[8:9], v[136:137]
	v_pk_mul_f32 v[24:25], v[24:25], v[136:137]
	v_pk_mul_f32 v[10:11], v[10:11], v[138:139]
	v_pk_mul_f32 v[26:27], v[26:27], v[138:139]
	v_pk_mul_f32 v[12:13], v[12:13], v[140:141]
	v_pk_mul_f32 v[28:29], v[28:29], v[140:141]
	v_pk_mul_f32 v[14:15], v[14:15], v[142:143]
	v_pk_mul_f32 v[30:31], v[30:31], v[142:143]
	v_pk_mul_f32 v[16:17], v[16:17], v[144:145]
	v_pk_mul_f32 v[32:33], v[32:33], v[144:145]
.Lfp_nors:
	s_and_b64 vcc, exec, s[2:3]
	s_cbranch_vccnz .Lfp_w0
	s_cmp_eq_u32 s87, 0
	s_cbranch_scc1 .Lfp_wt0
	s_and_b64 vcc, exec, s[92:93]
	s_cbranch_vccz .Lfp_w3
	s_waitcnt vmcnt(2)
	s_branch .Lfp_wd
.Lfp_w3:
	s_waitcnt vmcnt(3)
	s_branch .Lfp_wd
.Lfp_wt0:
	s_and_b64 vcc, exec, s[92:93]
	s_cbranch_vccz .Lfp_wt0b
	s_waitcnt vmcnt(1)
	s_branch .Lfp_wd
.Lfp_wt0b:
	s_waitcnt vmcnt(2)
	s_branch .Lfp_wd

; #define ATT_WAIT_TILE() do { if (FOX) { if (w == 0) asm volatile("s_waitcnt vmcnt(3)" ::: "memory"); else asm volatile("s_waitcnt vmcnt(2)" ::: "memory"); } \
;                              else asm volatile("s_waitcnt vmcnt(5)" ::: "memory"); } while (0)
; template <int DQK, int DV, bool FOX> ...
;     ...
;         if (t + 2 < NT) ATT_WAIT_TILE(); else asm volatile("s_waitcnt vmcnt(0)" ::: "memory");
;         asm volatile("s_waitcnt lgkmcnt(0)" ::: "memory");
;         __builtin_amdgcn_s_barrier();
;         bc = (bc == 2) ? 0 : bc + 1; bn2 = (bn2 == 2) ? 0 : bn2 + 1;
.Lfp_wd:
	s_waitcnt lgkmcnt(0)
	s_barrier
	s_branch .Lfp_latch

; __global__ void __launch_bounds__(512, 2) fwd_kernel(Args a) {
	.amdhsa_kernel _Z10fwd_kernel4Args
		.amdhsa_group_segment_fixed_size 0
		.amdhsa_private_segment_fixed_size 0
		.amdhsa_kernarg_size 432
		.amdhsa_user_sgpr_count 2
		.amdhsa_user_sgpr_dispatch_ptr 0
		.amdhsa_user_sgpr_queue_ptr 0
		.amdhsa_user_sgpr_kernarg_segment_ptr 1
		.amdhsa_user_sgpr_dispatch_id 0
		.amdhsa_user_sgpr_kernarg_preload_length 0
		.amdhsa_user_sgpr_kernarg_preload_offset 0
		.amdhsa_user_sgpr_private_segment_size 0
		.amdhsa_uses_dynamic_stack 0
		.amdhsa_enable_private_segment 0
		.amdhsa_system_sgpr_workgroup_id_x 1
		.amdhsa_system_sgpr_workgroup_id_y 0
		.amdhsa_system_sgpr_workgroup_id_z 0
		.amdhsa_system_sgpr_workgroup_info 0
		.amdhsa_system_vgpr_workitem_id 0
		.amdhsa_next_free_vgpr 256
		.amdhsa_next_free_sgpr 102
		.amdhsa_accum_offset 256
		.amdhsa_reserve_vcc 1
		.amdhsa_float_round_mode_32 0
		.amdhsa_float_round_mode_16_64 0
		.amdhsa_float_denorm_mode_32 3
		.amdhsa_float_denorm_mode_16_64 3
		.amdhsa_dx10_clamp 1
		.amdhsa_ieee_mode 1
		.amdhsa_fp16_overflow 0
		.amdhsa_tg_split 0
		.amdhsa_exception_fp_ieee_invalid_op 0
		.amdhsa_exception_fp_denorm_src 0
		.amdhsa_exception_fp_ieee_div_zero 0
		.amdhsa_exception_fp_ieee_overflow 0
		.amdhsa_exception_fp_ieee_underflow 0
		.amdhsa_exception_fp_ieee_inexact 0
		.amdhsa_exception_int_div_zero 0
	.end_amdhsa_kernel

; __global__ void __launch_bounds__(512, 2) fwd_kernel(Args a) {
amdhsa.kernels:
  - .agpr_count:     0
    .args:
      - .offset:         0
        .size:           176
        .value_kind:     by_value
      - .offset:         176
        .size:           4
        .value_kind:     hidden_block_count_x
      - .offset:         180
        .size:           4
        .value_kind:     hidden_block_count_y
      - .offset:         184
        .size:           4
        .value_kind:     hidden_block_count_z
      - .offset:         188
        .size:           2
        .value_kind:     hidden_group_size_x
      - .offset:         190
        .size:           2
        .value_kind:     hidden_group_size_y
      - .offset:         192
        .size:           2
        .value_kind:     hidden_group_size_z
      - .offset:         194
        .size:           2
        .value_kind:     hidden_remainder_x
      - .offset:         196
        .size:           2
        .value_kind:     hidden_remainder_y
      - .offset:         198
        .size:           2
        .value_kind:     hidden_remainder_z
      - .offset:         216
        .size:           8
        .value_kind:     hidden_global_offset_x
      - .offset:         224
        .size:           8
        .value_kind:     hidden_global_offset_y
      - .offset:         232
        .size:           8
        .value_kind:     hidden_global_offset_z
      - .offset:         240
        .size:           2
        .value_kind:     hidden_grid_dims
      - .offset:         264
        .size:           8
        .value_kind:     hidden_multigrid_sync_arg
      - .offset:         296
        .size:           4
        .value_kind:     hidden_dynamic_lds_size
    .group_segment_fixed_size: 0
    .kernarg_segment_align: 8
    .kernarg_segment_size: 432
    .language:       OpenCL C
    .language_version:
      - 2
      - 0
    .max_flat_workgroup_size: 512
    .name:           _Z10fwd_kernel4Args
    .private_segment_fixed_size: 0
    .sgpr_count:     108
    .sgpr_spill_count: 49
    .symbol:         _Z10fwd_kernel4Args.kd
    .uniform_work_group_size: 1
    .uses_dynamic_stack: false
    .vgpr_count:     256
    .vgpr_spill_count: 0
    .wavefront_size: 64
